# stack12: + V^T loop waits for loads only, attention prologue loads both Q passes together
# baseline (speedup 1.0000x reference)
; #define LAS __attribute__((address_space(3)))
;     ...
;     auto load_tile = [&](KVRegs& r, int t) {
;         const bf16* ks = Kp + (size_t)(t * 64 + kr) * ldkv; r.ka = *(const u32x4*)(ks + 8 * kj); r.kb = *(const u32x4*)(ks + 64 + 8 * kj);
;         if (MODE == 0) { const bf16* vs = Vp + (size_t)(tid >> 2) * SEQ + t * 64 + 16 * (tid & 3); r.va = *(const u32x4*)vs; r.vb = *(const u32x4*)(vs + 8); }
;         else { const bf16* vs = Vp + (size_t)(t * 64 + vr) * ldkv; r.va = *(const u32x4*)(vs + 8 * vj); r.vb = *(const u32x4*)(vs + 64 + 8 * vj); } };
;     auto stage = [&](KVRegs& r, int buf) {
;         LAS bf16* Ks = (LAS bf16*)(lds + koff(buf)); LAS bf16* VT = (LAS bf16*)(lds + voff(buf));
;         if (MODE >= 1) norm16(r.ka, r.kb, kg, 1.0f);
;         *(LAS u32x4*)(Ks + kr * QP + 8 * kj) = r.ka; *(LAS u32x4*)(Ks + kr * QP + 64 + 8 * kj) = r.kb;
;         if (MODE == 0) { *(LAS u32x4*)(VT + (tid >> 2) * VPA + 16 * (tid & 3)) = r.va; *(LAS u32x4*)(VT + (tid >> 2) * VPA + 16 * (tid & 3) + 8) = r.vb; }
;     ...
;     for (int p = 0; p < 2; ++p) {
;         const bf16* src = Qp + (size_t)(p * 64 + kr) * ldq;
;         u32x4 a = *(const u32x4*)(src + 8 * kj), b = *(const u32x4*)(src + 64 + 8 * kj);
;         if (MODE == 1) norm16(a, b, qg, QSCALE);
;         *(LAS u32x4*)(Qs + (p * 64 + kr) * QP + 8 * kj) = a; *(LAS u32x4*)(Qs + (p * 64 + kr) * QP + 64 + 8 * kj) = b;
;     }
;     }
;     stage(r0, 0); if (2 < ntiles) load_tile(r0, 2);
.LBB0_116:
	s_and_b64 s[58:59], s[40:41], exec
	v_mov_b32_e32 v155, v176
	s_cselect_b32 s58, s22, s23
	v_mov_b64_e32 v[4:5], s[36:37]
	v_ashrrev_i32_e32 v6, 3, v155
	v_and_b32_e32 v2, 7, v155
	s_or_b32 s76, s24, s58
	v_mad_i64_i32 v[0:1], s[74:75], v6, s97, v[4:5]
	v_lshlrev_b32_e32 v152, 4, v2
	v_ashrrev_i32_e32 v16, 2, v155
	v_lshlrev_b32_e32 v7, 4, v155
	s_mul_hi_u32 s63, s76, 0x3000
	s_mul_i32 s68, s25, 0x3000
	v_lshl_add_u64 v[0:1], v[0:1], 0, v[152:153]
	v_ashrrev_i32_e32 v17, 31, v16
	v_and_b32_e32 v7, 48, v7
	s_mul_i32 s59, s76, 0x3000
	s_add_i32 s63, s63, s68
	global_load_dwordx4 v[32:35], v[0:1], off offset:2048
	global_load_dwordx4 v[36:39], v[0:1], off offset:2176
	v_lshlrev_b64 v[0:1], 12, v[16:17]
	v_lshlrev_b32_e32 v148, 1, v7
	v_add_u32_e32 v7, 64, v6
	s_add_u32 s68, s26, s59
	v_lshlrev_b32_e32 v18, 3, v2
	v_lshl_add_u64 v[2:3], s[42:43], 0, v[0:1]
	v_mov_b32_e32 v149, v153
	v_mad_i64_i32 v[4:5], s[74:75], v7, s97, v[4:5]
	s_addc_u32 s69, s34, s63
	v_lshl_add_u64 v[2:3], v[2:3], 0, v[148:149]
	v_lshl_add_u64 v[4:5], v[4:5], 0, v[152:153]
	global_load_dwordx4 v[40:43], v[2:3], off offset:16
	global_load_dwordx4 v[44:47], v[2:3], off
	global_load_dwordx4 v[48:51], v[4:5], off offset:2048
	global_load_dwordx4 v[52:55], v[4:5], off offset:2176
	global_load_dwordx4 v[56:59], v[2:3], off offset:144
	global_load_dwordx4 v[60:63], v[2:3], off offset:128
	v_mov_b64_e32 v[4:5], s[68:69]
	v_mad_i64_i32 v[8:9], s[68:69], v6, s97, v[4:5]
	v_lshl_add_u64 v[12:13], v[8:9], 0, v[152:153]
	global_load_dwordx4 v[8:11], v[12:13], off
	s_nop 0
	global_load_dwordx4 v[12:15], v[12:13], off offset:128
	v_mul_lo_u32 v149, v6, s94
	v_add3_u32 v17, s92, v149, v152
	v_mad_i64_i32 v[4:5], s[68:69], v7, s97, v[4:5]
	v_lshl_add_u64 v[4:5], v[4:5], 0, v[152:153]
	global_load_dwordx4 v[64:67], v[4:5], off
	global_load_dwordx4 v[68:71], v[4:5], off offset:128
	v_mul_lo_u32 v157, v16, s31
	s_cmp_lg_u32 s58, 0
	s_cselect_b64 s[74:75], -1, 0
	s_cmp_eq_u32 s58, 0
	s_waitcnt vmcnt(3)
	ds_write_b128 v17, v[8:11]
	s_waitcnt vmcnt(2)
	ds_write_b128 v17, v[12:15] offset:128
	v_add_u32_e32 v4, 0, v149
	v_add_u32_e32 v7, v4, v152
	v_lshlrev_b32_e32 v4, 1, v18
	s_waitcnt vmcnt(1)
	ds_write_b128 v17, v[64:67] offset:18432
	s_waitcnt vmcnt(0)
	ds_write_b128 v17, v[68:71] offset:18560
	v_add3_u32 v8, 0, v157, v148
	ds_write_b128 v7, v[32:35]
	ds_write_b128 v7, v[36:39] offset:128
	ds_write_b128 v8, v[44:47] offset:18432
	ds_write_b128 v8, v[40:43] offset:18448
	s_cbranch_scc1 .LBB0_118
	v_add_u32_e32 v5, 0x80, v6
	v_mov_b64_e32 v[10:11], s[36:37]
	v_mad_i64_i32 v[10:11], s[68:69], v5, s97, v[10:11]
	v_mov_b32_e32 v5, v153
	v_lshl_add_u64 v[10:11], v[10:11], 0, v[4:5]
	global_load_dwordx4 v[32:35], v[10:11], off offset:2048
	global_load_dwordx4 v[36:39], v[10:11], off offset:2176
	global_load_dwordx4 v[40:43], v[2:3], off offset:272
	global_load_dwordx4 v[44:47], v[2:3], off offset:256

; #define LAS __attribute__((address_space(3)))
; __global__ void __launch_bounds__(512, 2) fwd_mega(Args args) {
;     ...
;             { LAS bf16* T = (LAS bf16*)lds; const int r = tid >> 3, j = tid & 7, dd = tid & 127, kq = tid >> 7;
;               int idx = bx; u32x4 ta = {0u, 0u, 0u, 0u}, tb = {0u, 0u, 0u, 0u};
;               if (idx < 2048) { const int rem = idx & 1023, b_ = rem >> 8, hq = (rem >> 5) & 7, st = rem & 31; const bf16* p = PROJ + (size_t)(b_ * SEQ + 64 * st + r) * PROJW + ((idx >> 10) ? 4096 : 2048) + 128 * hq + 8 * j;
;                   ta = *(const u32x4*)p; tb = *(const u32x4*)(p + 64); }
.LBB0_141:
	v_readlane_b32 s10, v253, 10
	v_readlane_b32 s11, v253, 11
	s_andn2_b64 vcc, exec, s[10:11]
	s_cbranch_vccnz .LBB0_153
	v_ashrrev_i32_e32 v9, 3, v238
	v_readlane_b32 s0, v253, 14
	v_mov_b64_e32 v[0:1], s[38:39]
	v_and_b32_e32 v8, 7, v238
	v_add_u32_e32 v2, s0, v9
	v_mad_i64_i32 v[0:1], s[10:11], v2, s97, v[0:1]
	v_readlane_b32 s10, v255, 21
	s_mov_b32 s0, s10
	v_readlane_b32 s11, v255, 22
	v_writelane_b32 v255, s0, 21
	s_mov_b32 s11, s27
	v_lshl_add_u64 v[0:1], v[0:1], 0, s[10:11]
	v_writelane_b32 v255, s1, 22
	v_lshlrev_b32_e32 v152, 4, v8
	v_readlane_b32 s10, v255, 23
	v_readlane_b32 s11, v255, 24
	s_mov_b32 s11, s27
	v_ashrrev_i32_e32 v11, 7, v238
	v_lshl_add_u64 v[0:1], v[0:1], 0, s[10:11]
	v_lshl_add_u64 v[4:5], v[0:1], 0, v[152:153]
	global_load_dwordx4 v[0:3], v[4:5], off
	s_nop 0
	global_load_dwordx4 v[4:7], v[4:5], off offset:128
	s_mov_b32 s0, s10
	v_lshlrev_b32_e32 v10, 4, v11
	v_and_b32_e32 v15, 0xffffffe0, v9
	v_lshlrev_b32_e32 v11, 3, v11
	v_writelane_b32 v255, s0, 23
	v_and_b32_e32 v13, 0x7f, v238
	v_lshlrev_b32_e32 v12, 3, v8
	v_mul_lo_u32 v8, v9, s94
	v_and_or_b32 v15, v11, 8, v15
	v_writelane_b32 v255, s1, 24
	v_add3_u32 v14, 0, v8, v152
	v_lshl_add_u32 v8, v13, 1, 0
	v_lshlrev_b32_e32 v16, 11, v13
	v_ashrrev_i32_e32 v11, 31, v10
	v_or_b32_e32 v17, 4, v10
	v_or_b32_e32 v18, 16, v15
	v_or_b32_e32 v19, 5, v10
	v_or_b32_e32 v20, 17, v15
	v_or_b32_e32 v21, 6, v10
	v_or_b32_e32 v22, 18, v15
	v_or_b32_e32 v23, 7, v10
	v_or_b32_e32 v24, 19, v15
	v_or_b32_e32 v25, 8, v10
	v_or_b32_e32 v26, 4, v15
	v_or_b32_e32 v27, 9, v10
	v_or_b32_e32 v28, 5, v15
	v_or_b32_e32 v29, 10, v10
	v_or_b32_e32 v30, 6, v15
	v_or_b32_e32 v31, 11, v10
	v_or_b32_e32 v32, 7, v15
	v_or_b32_e32 v33, 12, v10
	v_or_b32_e32 v34, 20, v15
	v_or_b32_e32 v35, 13, v10
	v_or_b32_e32 v36, 21, v15
	v_or_b32_e32 v37, 14, v10
	v_or_b32_e32 v38, 22, v15
	v_or_b32_e32 v39, 15, v10
	s_waitcnt vmcnt(3)
	v_or_b32_e32 v40, 23, v15
	v_lshlrev_b32_e32 v12, 1, v12
	v_readlane_b32 s0, v254, 59
	v_readlane_b32 s14, v254, 54
	v_readlane_b32 s16, v253, 13
	v_readlane_b32 s15, v254, 53
	s_mov_b32 s23, s2
	s_waitcnt vmcnt(0)
	s_branch .LBB0_144

; #define LAS __attribute__((address_space(3)))
; __global__ void __launch_bounds__(512, 2) fwd_mega(Args args) {
;     ...
;               for (; idx < 2048; idx += G) {
;                   *(LAS u32x4*)(T + r * QP + 8 * j) = ta; *(LAS u32x4*)(T + r * QP + 64 + 8 * j) = tb;
;                   __syncthreads();
.LBB0_144:
	s_add_i32 s17, s23, s52
	s_cmpk_gt_i32 s17, 0x7ff
	s_cselect_b64 s[10:11], -1, 0
	s_cmpk_lt_i32 s17, 0x800
	s_mov_b64 s[24:25], -1
	s_waitcnt vmcnt(3)
	ds_write_b128 v14, v[0:3]
	s_waitcnt vmcnt(2)
	ds_write_b128 v14, v[4:7] offset:128
	s_waitcnt lgkmcnt(0)
	s_barrier
	s_cbranch_scc1 .LBB0_146
	v_readlane_b32 s22, v254, 57
	s_add_i32 s22, s16, s22
	s_mov_b64 s[24:25], 0
